# quarter (128x128) units of P5/P6 stop staging and reading the unused A/B half tiles (scalar-skipped LDS-DMA loads and ds_reads, stricter counted waits on that path)
# speedup vs baseline: 1.0380x; 1.0109x over previous
.LBB0_1132:
	ds_read_b128 v[148:151], v214
	ds_read_b128 v[152:155], v214 offset:1024
	ds_read_b128 v[156:159], v214 offset:2048
	ds_read_b128 v[160:163], v214 offset:3072
	s_mov_b64 exec, s[26:27]
	s_cbranch_execz .Lq5_r1
	ds_read_b128 v[132:135], v215
	ds_read_b128 v[136:139], v215 offset:1024
	ds_read_b128 v[140:143], v215 offset:2048
	ds_read_b128 v[144:147], v215 offset:3072
.Lq5_r1:
	s_mov_b64 exec, -1
	v_lshl_add_u64 v[2:3], s[34:35], 0, v[200:201]
	s_add_i32 m0, s48, 0xc000
	s_waitcnt lgkmcnt(0)
	ds_read_b128 v[188:191], v216
	ds_read_b128 v[192:195], v216 offset:1024
	ds_read_b128 v[180:183], v216 offset:2048
	ds_read_b128 v[184:187], v216 offset:3072
	ds_read_b128 v[172:175], v216 offset:4096
	ds_read_b128 v[176:179], v216 offset:5120
	ds_read_b128 v[164:167], v216 offset:6144
	ds_read_b128 v[168:171], v216 offset:7168
	s_mov_b64 exec, s[26:27]
	s_cbranch_execz .Lq5_s1
	global_load_lds_dwordx4 v[2:3], off
.Lq5_s1:
	s_mov_b64 exec, -1
	v_lshl_add_u64 v[2:3], s[34:35], 0, v[202:203]
	s_add_i32 m0, s48, 0xe000
	s_nop 0
	s_mov_b64 exec, s[26:27]
	s_cbranch_execz .Lq5_s2
	global_load_lds_dwordx4 v[2:3], off
.Lq5_s2:
	s_mov_b64 exec, -1
	s_waitcnt vmcnt(8)
	s_cmp_eq_u64 s[26:27], 0
	s_cbranch_scc0 .Lq5_w1
	s_waitcnt vmcnt(4)
.Lq5_w1:
	s_waitcnt lgkmcnt(0)
	s_barrier
	s_setprio 1
	s_waitcnt lgkmcnt(0)
	v_mfma_f32_16x16x32_bf16 v[128:131], v[148:151], v[188:191], v[128:131]
	v_mfma_f32_16x16x32_bf16 v[124:127], v[156:159], v[188:191], v[124:127]
	v_mfma_f32_16x16x32_bf16 v[120:123], v[148:151], v[180:183], v[120:123]
	v_mfma_f32_16x16x32_bf16 v[116:119], v[156:159], v[180:183], v[116:119]
	v_mfma_f32_16x16x32_bf16 v[104:107], v[148:151], v[172:175], v[104:107]
	v_mfma_f32_16x16x32_bf16 v[100:103], v[156:159], v[172:175], v[100:103]
	v_mfma_f32_16x16x32_bf16 v[88:91], v[148:151], v[164:167], v[88:91]
	v_mfma_f32_16x16x32_bf16 v[84:87], v[156:159], v[164:167], v[84:87]
	v_mfma_f32_16x16x32_bf16 v[128:131], v[152:155], v[192:195], v[128:131]
	v_mfma_f32_16x16x32_bf16 v[124:127], v[160:163], v[192:195], v[124:127]
	v_mfma_f32_16x16x32_bf16 v[120:123], v[152:155], v[184:187], v[120:123]
	v_mfma_f32_16x16x32_bf16 v[116:119], v[160:163], v[184:187], v[116:119]
	v_mfma_f32_16x16x32_bf16 v[104:107], v[152:155], v[176:179], v[104:107]
	v_mfma_f32_16x16x32_bf16 v[100:103], v[160:163], v[176:179], v[100:103]
	v_mfma_f32_16x16x32_bf16 v[88:91], v[152:155], v[168:171], v[88:91]
	v_mfma_f32_16x16x32_bf16 v[84:87], v[160:163], v[168:171], v[84:87]
	s_setprio 0
	v_cmp_ne_u32_e64 s[2:3], 1, v217
	s_andn2_b64 vcc, exec, s[26:27]
	s_cbranch_vccnz .LBB0_1134
	s_setprio 1
	v_mfma_f32_16x16x32_bf16 v[112:115], v[132:135], v[188:191], v[112:115]
	v_mfma_f32_16x16x32_bf16 v[108:111], v[140:143], v[188:191], v[108:111]
	v_mfma_f32_16x16x32_bf16 v[96:99], v[132:135], v[180:183], v[96:99]
	v_mfma_f32_16x16x32_bf16 v[92:95], v[140:143], v[180:183], v[92:95]
	v_mfma_f32_16x16x32_bf16 v[80:83], v[132:135], v[172:175], v[80:83]
	v_mfma_f32_16x16x32_bf16 v[76:79], v[140:143], v[172:175], v[76:79]
	v_mfma_f32_16x16x32_bf16 v[72:75], v[132:135], v[164:167], v[72:75]
	v_mfma_f32_16x16x32_bf16 v[68:71], v[140:143], v[164:167], v[68:71]
	v_mfma_f32_16x16x32_bf16 v[112:115], v[136:139], v[192:195], v[112:115]
	v_mfma_f32_16x16x32_bf16 v[108:111], v[144:147], v[192:195], v[108:111]
	v_mfma_f32_16x16x32_bf16 v[96:99], v[136:139], v[184:187], v[96:99]
	v_mfma_f32_16x16x32_bf16 v[92:95], v[144:147], v[184:187], v[92:95]
	v_mfma_f32_16x16x32_bf16 v[80:83], v[136:139], v[176:179], v[80:83]
	v_mfma_f32_16x16x32_bf16 v[76:79], v[144:147], v[176:179], v[76:79]
	v_mfma_f32_16x16x32_bf16 v[72:75], v[136:139], v[168:171], v[72:75]
	v_mfma_f32_16x16x32_bf16 v[68:71], v[144:147], v[168:171], v[68:71]
	s_setprio 0
.LBB0_1134:
	s_add_u32 s56, s34, 0xfff80080
	s_addc_u32 s57, s35, -1
	s_cmp_eq_u32 s77, 12
	s_cselect_b32 s59, s39, s57
	s_cselect_b32 s58, s38, s56
	s_cselect_b32 s57, s47, s41
	s_cselect_b32 s56, s46, s18
	s_barrier
	s_mov_b32 m0, s49
	v_lshl_add_u64 v[2:3], s[56:57], 0, v[198:199]
	s_add_u32 s78, s56, 0x80000
	s_mov_b64 exec, s[26:27]
	s_cbranch_execz .Lq5_r2
	ds_read_b128 v[188:191], v216 offset:16384
	ds_read_b128 v[192:195], v216 offset:17408
	ds_read_b128 v[180:183], v216 offset:18432
	ds_read_b128 v[184:187], v216 offset:19456
	ds_read_b128 v[172:175], v216 offset:20480
	ds_read_b128 v[176:179], v216 offset:21504
	ds_read_b128 v[164:167], v216 offset:22528
	ds_read_b128 v[168:171], v216 offset:23552
.Lq5_r2:
	s_mov_b64 exec, -1
	global_load_lds_dwordx4 v[2:3], off
	v_lshl_add_u64 v[204:205], s[56:57], 0, v[196:197]
	s_mov_b32 m0, s50
	s_addc_u32 s79, s57, 0
	global_load_lds_dwordx4 v[204:205], off
	v_lshl_add_u64 v[206:207], s[78:79], 0, v[198:199]
	s_mov_b32 m0, s51
	v_lshl_add_u64 v[208:209], s[58:59], 0, v[196:197]
	s_mov_b64 exec, s[26:27]
	s_cbranch_execz .Lq5_s3
	global_load_lds_dwordx4 v[206:207], off
.Lq5_s3:
	s_mov_b64 exec, -1
	v_lshl_add_u64 v[206:207], s[78:79], 0, v[196:197]
	s_mov_b32 m0, s60
	s_and_b64 vcc, exec, s[2:3]
	s_mov_b64 exec, s[26:27]
	s_cbranch_execz .Lq5_s4
	global_load_lds_dwordx4 v[206:207], off
.Lq5_s4:
	s_mov_b64 exec, -1
	v_lshl_add_u64 v[206:207], s[58:59], 0, v[198:199]
	s_mov_b32 m0, s48
	s_nop 0
	global_load_lds_dwordx4 v[206:207], off
	s_mov_b32 m0, s61
	s_nop 0
	global_load_lds_dwordx4 v[208:209], off
	s_waitcnt vmcnt(8)
	s_cmp_eq_u64 s[26:27], 0
	s_cbranch_scc0 .Lq5_w2
	s_waitcnt vmcnt(4)
.Lq5_w2:
	s_waitcnt lgkmcnt(0)
	s_barrier
	s_cbranch_vccnz .LBB0_1136
	s_setprio 1
	s_waitcnt lgkmcnt(0)
	v_mfma_f32_16x16x32_bf16 v[64:67], v[148:151], v[188:191], v[64:67]
	v_mfma_f32_16x16x32_bf16 v[60:63], v[156:159], v[188:191], v[60:63]
	v_mfma_f32_16x16x32_bf16 v[48:51], v[148:151], v[180:183], v[48:51]
	v_mfma_f32_16x16x32_bf16 v[44:47], v[156:159], v[180:183], v[44:47]
	v_mfma_f32_16x16x32_bf16 v[32:35], v[148:151], v[172:175], v[32:35]
	v_mfma_f32_16x16x32_bf16 v[28:31], v[156:159], v[172:175], v[28:31]
	v_mfma_f32_16x16x32_bf16 v[16:19], v[148:151], v[164:167], v[16:19]
	v_mfma_f32_16x16x32_bf16 v[12:15], v[156:159], v[164:167], v[12:15]
	v_mfma_f32_16x16x32_bf16 v[64:67], v[152:155], v[192:195], v[64:67]
	v_mfma_f32_16x16x32_bf16 v[60:63], v[160:163], v[192:195], v[60:63]
	v_mfma_f32_16x16x32_bf16 v[48:51], v[152:155], v[184:187], v[48:51]
	v_mfma_f32_16x16x32_bf16 v[44:47], v[160:163], v[184:187], v[44:47]
	v_mfma_f32_16x16x32_bf16 v[32:35], v[152:155], v[176:179], v[32:35]
	v_mfma_f32_16x16x32_bf16 v[28:31], v[160:163], v[176:179], v[28:31]
	v_mfma_f32_16x16x32_bf16 v[16:19], v[152:155], v[168:171], v[16:19]
	v_mfma_f32_16x16x32_bf16 v[12:15], v[160:163], v[168:171], v[12:15]
	s_setprio 0
	s_setprio 1
	v_mfma_f32_16x16x32_bf16 v[56:59], v[132:135], v[188:191], v[56:59]
	v_mfma_f32_16x16x32_bf16 v[52:55], v[140:143], v[188:191], v[52:55]
	v_mfma_f32_16x16x32_bf16 v[40:43], v[132:135], v[180:183], v[40:43]
	v_mfma_f32_16x16x32_bf16 v[36:39], v[140:143], v[180:183], v[36:39]
	v_mfma_f32_16x16x32_bf16 v[24:27], v[132:135], v[172:175], v[24:27]
	v_mfma_f32_16x16x32_bf16 v[20:23], v[140:143], v[172:175], v[20:23]
	v_mfma_f32_16x16x32_bf16 v[8:11], v[132:135], v[164:167], v[8:11]
	v_mfma_f32_16x16x32_bf16 v[4:7], v[140:143], v[164:167], v[4:7]
	v_mfma_f32_16x16x32_bf16 v[56:59], v[136:139], v[192:195], v[56:59]
	v_mfma_f32_16x16x32_bf16 v[52:55], v[144:147], v[192:195], v[52:55]
	v_mfma_f32_16x16x32_bf16 v[40:43], v[136:139], v[184:187], v[40:43]
	v_mfma_f32_16x16x32_bf16 v[36:39], v[144:147], v[184:187], v[36:39]
	v_mfma_f32_16x16x32_bf16 v[24:27], v[136:139], v[176:179], v[24:27]
	v_mfma_f32_16x16x32_bf16 v[20:23], v[144:147], v[176:179], v[20:23]
	v_mfma_f32_16x16x32_bf16 v[8:11], v[136:139], v[168:171], v[8:11]
	v_mfma_f32_16x16x32_bf16 v[4:7], v[144:147], v[168:171], v[4:7]
	s_setprio 0
.LBB0_1136:
	s_barrier
	v_add_u32_e32 v1, 0x18000, v213
	ds_read_b128 v[148:151], v1
	ds_read_b128 v[152:155], v1 offset:1024
	ds_read_b128 v[156:159], v1 offset:2048
	ds_read_b128 v[160:163], v1 offset:3072
	v_add_u32_e32 v1, 0x1c000, v213
	s_mov_b64 exec, s[26:27]
	s_cbranch_execz .Lq5_r3
	ds_read_b128 v[132:135], v1
	ds_read_b128 v[136:139], v1 offset:1024
	ds_read_b128 v[140:143], v1 offset:2048
	ds_read_b128 v[144:147], v1 offset:3072
.Lq5_r3:
	s_mov_b64 exec, -1
	s_add_u32 s58, s58, 0x80000
	s_addc_u32 s59, s59, 0
	s_mov_b32 m0, s62
	v_lshl_add_u64 v[218:219], s[58:59], 0, v[198:199]
	s_waitcnt lgkmcnt(0)
	ds_read_b128 v[188:191], v216 offset:32768
	ds_read_b128 v[192:195], v216 offset:33792
	ds_read_b128 v[180:183], v216 offset:34816
	ds_read_b128 v[184:187], v216 offset:35840
	ds_read_b128 v[172:175], v216 offset:36864
	ds_read_b128 v[176:179], v216 offset:37888
	ds_read_b128 v[164:167], v216 offset:38912
	ds_read_b128 v[168:171], v216 offset:39936
	s_mov_b64 exec, s[26:27]
	s_cbranch_execz .Lq5_s5
	global_load_lds_dwordx4 v[218:219], off
.Lq5_s5:
	s_mov_b64 exec, -1
	v_lshl_add_u64 v[218:219], s[58:59], 0, v[196:197]
	s_mov_b32 m0, s63
	s_nop 0
	s_mov_b64 exec, s[26:27]
	s_cbranch_execz .Lq5_s6
	global_load_lds_dwordx4 v[218:219], off

.Lq5_w3:
	s_waitcnt lgkmcnt(0)
	s_barrier
	s_setprio 1
	s_waitcnt lgkmcnt(0)
	v_mfma_f32_16x16x32_bf16 v[128:131], v[148:151], v[188:191], v[128:131]
	v_mfma_f32_16x16x32_bf16 v[124:127], v[156:159], v[188:191], v[124:127]
	v_mfma_f32_16x16x32_bf16 v[120:123], v[148:151], v[180:183], v[120:123]
	v_mfma_f32_16x16x32_bf16 v[116:119], v[156:159], v[180:183], v[116:119]
	v_mfma_f32_16x16x32_bf16 v[104:107], v[148:151], v[172:175], v[104:107]
	v_mfma_f32_16x16x32_bf16 v[100:103], v[156:159], v[172:175], v[100:103]
	v_mfma_f32_16x16x32_bf16 v[88:91], v[148:151], v[164:167], v[88:91]
	v_mfma_f32_16x16x32_bf16 v[84:87], v[156:159], v[164:167], v[84:87]
	v_mfma_f32_16x16x32_bf16 v[128:131], v[152:155], v[192:195], v[128:131]
	v_mfma_f32_16x16x32_bf16 v[124:127], v[160:163], v[192:195], v[124:127]
	v_mfma_f32_16x16x32_bf16 v[120:123], v[152:155], v[184:187], v[120:123]
	v_mfma_f32_16x16x32_bf16 v[116:119], v[160:163], v[184:187], v[116:119]
	v_mfma_f32_16x16x32_bf16 v[104:107], v[152:155], v[176:179], v[104:107]
	v_mfma_f32_16x16x32_bf16 v[100:103], v[160:163], v[176:179], v[100:103]
	v_mfma_f32_16x16x32_bf16 v[88:91], v[152:155], v[168:171], v[88:91]
	v_mfma_f32_16x16x32_bf16 v[84:87], v[160:163], v[168:171], v[84:87]
	s_setprio 0
	s_and_b64 vcc, exec, s[2:3]
	s_cbranch_vccnz .LBB0_1138
	s_setprio 1
	v_mfma_f32_16x16x32_bf16 v[112:115], v[132:135], v[188:191], v[112:115]
	v_mfma_f32_16x16x32_bf16 v[108:111], v[140:143], v[188:191], v[108:111]
	v_mfma_f32_16x16x32_bf16 v[96:99], v[132:135], v[180:183], v[96:99]
	v_mfma_f32_16x16x32_bf16 v[92:95], v[140:143], v[180:183], v[92:95]
	v_mfma_f32_16x16x32_bf16 v[80:83], v[132:135], v[172:175], v[80:83]
	v_mfma_f32_16x16x32_bf16 v[76:79], v[140:143], v[172:175], v[76:79]
	v_mfma_f32_16x16x32_bf16 v[72:75], v[132:135], v[164:167], v[72:75]
	v_mfma_f32_16x16x32_bf16 v[68:71], v[140:143], v[164:167], v[68:71]
	v_mfma_f32_16x16x32_bf16 v[112:115], v[136:139], v[192:195], v[112:115]
	v_mfma_f32_16x16x32_bf16 v[108:111], v[144:147], v[192:195], v[108:111]
	v_mfma_f32_16x16x32_bf16 v[96:99], v[136:139], v[184:187], v[96:99]
	v_mfma_f32_16x16x32_bf16 v[92:95], v[144:147], v[184:187], v[92:95]
	v_mfma_f32_16x16x32_bf16 v[80:83], v[136:139], v[176:179], v[80:83]
	v_mfma_f32_16x16x32_bf16 v[76:79], v[144:147], v[176:179], v[76:79]
	v_mfma_f32_16x16x32_bf16 v[72:75], v[136:139], v[168:171], v[72:75]
	v_mfma_f32_16x16x32_bf16 v[68:71], v[144:147], v[168:171], v[68:71]
	s_setprio 0
.LBB0_1138:
	s_barrier
	s_mov_b32 m0, s66
	v_lshl_add_u64 v[2:3], v[2:3], 0, s[16:17]
	s_add_u32 s56, s56, 0x80080
	s_mov_b64 exec, s[26:27]
	s_cbranch_execz .Lq5_r4
	ds_read_b128 v[188:191], v216 offset:49152
	ds_read_b128 v[192:195], v216 offset:50176
	ds_read_b128 v[180:183], v216 offset:51200
	ds_read_b128 v[184:187], v216 offset:52224
	ds_read_b128 v[172:175], v216 offset:53248
	ds_read_b128 v[176:179], v216 offset:54272
	ds_read_b128 v[164:167], v216 offset:55296
	ds_read_b128 v[168:171], v216 offset:56320
.Lq5_r4:
	s_mov_b64 exec, -1
	global_load_lds_dwordx4 v[2:3], off
	v_lshl_add_u64 v[2:3], v[204:205], 0, s[16:17]
	s_mov_b32 m0, s67
	s_addc_u32 s57, s57, 0
	global_load_lds_dwordx4 v[2:3], off
	v_lshl_add_u64 v[2:3], s[56:57], 0, v[198:199]
	s_mov_b32 m0, s70
	s_and_b64 vcc, exec, s[2:3]
	s_mov_b64 exec, s[26:27]
	s_cbranch_execz .Lq5_s7
	global_load_lds_dwordx4 v[2:3], off
.Lq5_s7:
	s_mov_b64 exec, -1
	v_lshl_add_u64 v[2:3], s[56:57], 0, v[196:197]
	s_mov_b32 m0, s71
	s_nop 0
	s_mov_b64 exec, s[26:27]
	s_cbranch_execz .Lq5_s8
	global_load_lds_dwordx4 v[2:3], off
.Lq5_s8:
	s_mov_b64 exec, -1
	v_lshl_add_u64 v[2:3], v[206:207], 0, s[16:17]
	s_mov_b32 m0, s68
	s_nop 0
	global_load_lds_dwordx4 v[2:3], off
	v_lshl_add_u64 v[2:3], v[208:209], 0, s[16:17]
	s_mov_b32 m0, s69
	s_nop 0
	global_load_lds_dwordx4 v[2:3], off
	s_waitcnt vmcnt(8)
	s_cmp_eq_u64 s[26:27], 0
	s_cbranch_scc0 .Lq5_w4
	s_waitcnt vmcnt(4)
.Lq5_w4:
	s_waitcnt lgkmcnt(0)
	s_barrier
	s_cbranch_vccnz .LBB0_1131
	s_setprio 1
	s_waitcnt lgkmcnt(0)
	v_mfma_f32_16x16x32_bf16 v[64:67], v[148:151], v[188:191], v[64:67]
	v_mfma_f32_16x16x32_bf16 v[60:63], v[156:159], v[188:191], v[60:63]
	v_mfma_f32_16x16x32_bf16 v[48:51], v[148:151], v[180:183], v[48:51]
	v_mfma_f32_16x16x32_bf16 v[44:47], v[156:159], v[180:183], v[44:47]
	v_mfma_f32_16x16x32_bf16 v[32:35], v[148:151], v[172:175], v[32:35]
	v_mfma_f32_16x16x32_bf16 v[28:31], v[156:159], v[172:175], v[28:31]
	v_mfma_f32_16x16x32_bf16 v[16:19], v[148:151], v[164:167], v[16:19]
	v_mfma_f32_16x16x32_bf16 v[12:15], v[156:159], v[164:167], v[12:15]
	v_mfma_f32_16x16x32_bf16 v[64:67], v[152:155], v[192:195], v[64:67]
	v_mfma_f32_16x16x32_bf16 v[60:63], v[160:163], v[192:195], v[60:63]
	v_mfma_f32_16x16x32_bf16 v[48:51], v[152:155], v[184:187], v[48:51]
	v_mfma_f32_16x16x32_bf16 v[44:47], v[160:163], v[184:187], v[44:47]
	v_mfma_f32_16x16x32_bf16 v[32:35], v[152:155], v[176:179], v[32:35]
	v_mfma_f32_16x16x32_bf16 v[28:31], v[160:163], v[176:179], v[28:31]
	v_mfma_f32_16x16x32_bf16 v[16:19], v[152:155], v[168:171], v[16:19]
	v_mfma_f32_16x16x32_bf16 v[12:15], v[160:163], v[168:171], v[12:15]
	s_setprio 0
	s_setprio 1
	v_mfma_f32_16x16x32_bf16 v[56:59], v[132:135], v[188:191], v[56:59]
	v_mfma_f32_16x16x32_bf16 v[52:55], v[140:143], v[188:191], v[52:55]
	v_mfma_f32_16x16x32_bf16 v[40:43], v[132:135], v[180:183], v[40:43]
	v_mfma_f32_16x16x32_bf16 v[36:39], v[140:143], v[180:183], v[36:39]
	v_mfma_f32_16x16x32_bf16 v[24:27], v[132:135], v[172:175], v[24:27]
	v_mfma_f32_16x16x32_bf16 v[20:23], v[140:143], v[172:175], v[20:23]
	v_mfma_f32_16x16x32_bf16 v[8:11], v[132:135], v[164:167], v[8:11]
	v_mfma_f32_16x16x32_bf16 v[2:5], v[140:143], v[164:167], v[4:7]
	v_mfma_f32_16x16x32_bf16 v[56:59], v[136:139], v[192:195], v[56:59]
	v_mfma_f32_16x16x32_bf16 v[52:55], v[144:147], v[192:195], v[52:55]
	v_mfma_f32_16x16x32_bf16 v[40:43], v[136:139], v[184:187], v[40:43]
	v_mfma_f32_16x16x32_bf16 v[36:39], v[144:147], v[184:187], v[36:39]
	v_mfma_f32_16x16x32_bf16 v[24:27], v[136:139], v[176:179], v[24:27]
	v_mfma_f32_16x16x32_bf16 v[20:23], v[144:147], v[176:179], v[20:23]
	v_mfma_f32_16x16x32_bf16 v[8:11], v[136:139], v[168:171], v[8:11]
	v_mfma_f32_16x16x32_bf16 v[4:7], v[144:147], v[168:171], v[2:5]
	s_setprio 0
	s_branch .LBB0_1131

.LBB0_1283:
	ds_read_b128 v[180:183], v247
	ds_read_b128 v[184:187], v247 offset:1024
	ds_read_b128 v[188:191], v247 offset:2048
	ds_read_b128 v[192:195], v247 offset:3072
	s_mov_b64 exec, s[34:35]
	s_cbranch_execz .Lq6_r1
	ds_read_b128 v[164:167], v248
	ds_read_b128 v[168:171], v248 offset:1024
	ds_read_b128 v[172:175], v248 offset:2048
	ds_read_b128 v[176:179], v248 offset:3072
.Lq6_r1:
	s_mov_b64 exec, -1
	v_lshl_add_u64 v[2:3], s[38:39], 0, v[232:233]
	s_add_i32 m0, s44, 0xc000
	ds_read_b128 v[220:223], v249
	ds_read_b128 v[224:227], v249 offset:1024
	ds_read_b128 v[212:215], v249 offset:2048
	ds_read_b128 v[216:219], v249 offset:3072
	ds_read_b128 v[204:207], v249 offset:4096
	ds_read_b128 v[208:211], v249 offset:5120
	ds_read_b128 v[196:199], v249 offset:6144
	ds_read_b128 v[200:203], v249 offset:7168
	s_mov_b64 exec, s[34:35]
	s_cbranch_execz .Lq6_s1
	global_load_lds_dwordx4 v[2:3], off
.Lq6_s1:
	s_mov_b64 exec, -1
	v_lshl_add_u64 v[2:3], s[38:39], 0, v[234:235]
	s_add_i32 m0, s44, 0xe000
	s_nop 0
	s_mov_b64 exec, s[34:35]
	s_cbranch_execz .Lq6_s2
	global_load_lds_dwordx4 v[2:3], off
.Lq6_s2:
	s_mov_b64 exec, -1
	s_waitcnt vmcnt(8)
	s_cmp_eq_u64 s[34:35], 0
	s_cbranch_scc0 .Lq6_w1
	s_waitcnt vmcnt(4)
.Lq6_w1:
	s_waitcnt lgkmcnt(0)
	s_barrier
	s_setprio 1
	s_waitcnt lgkmcnt(0)
	v_mfma_f32_16x16x32_bf16 v[68:71], v[180:183], v[220:223], v[160:163]
	v_mfma_f32_16x16x32_bf16 v[72:75], v[188:191], v[220:223], v[156:159]
	v_mfma_f32_16x16x32_bf16 v[76:79], v[180:183], v[212:215], v[152:155]
	v_mfma_f32_16x16x32_bf16 v[80:83], v[188:191], v[212:215], v[148:151]
	v_mfma_f32_16x16x32_bf16 v[84:87], v[180:183], v[204:207], v[136:139]
	v_mfma_f32_16x16x32_bf16 v[92:95], v[188:191], v[204:207], v[132:135]
	v_mfma_f32_16x16x32_bf16 v[96:99], v[180:183], v[196:199], v[120:123]
	v_mfma_f32_16x16x32_bf16 v[100:103], v[188:191], v[196:199], v[112:115]
	v_mfma_f32_16x16x32_bf16 v[68:71], v[184:187], v[224:227], v[68:71]
	v_mfma_f32_16x16x32_bf16 v[72:75], v[192:195], v[224:227], v[72:75]
	v_mfma_f32_16x16x32_bf16 v[76:79], v[184:187], v[216:219], v[76:79]
	v_mfma_f32_16x16x32_bf16 v[80:83], v[192:195], v[216:219], v[80:83]
	v_mfma_f32_16x16x32_bf16 v[84:87], v[184:187], v[208:211], v[84:87]
	v_mfma_f32_16x16x32_bf16 v[92:95], v[192:195], v[208:211], v[92:95]
	v_mfma_f32_16x16x32_bf16 v[96:99], v[184:187], v[200:203], v[96:99]
	v_mfma_f32_16x16x32_bf16 v[100:103], v[192:195], v[200:203], v[100:103]
	s_setprio 0
	v_cmp_ne_u32_e64 s[4:5], 1, v251
	s_andn2_b64 vcc, exec, s[34:35]
	s_cbranch_vccnz .LBB0_1285
	s_setprio 1
	v_mfma_f32_16x16x32_bf16 v[112:115], v[164:167], v[220:223], v[144:147]
	v_mfma_f32_16x16x32_bf16 v[144:147], v[168:171], v[224:227], v[112:115]
	v_mfma_f32_16x16x32_bf16 v[112:115], v[172:175], v[220:223], v[140:143]
	v_mfma_f32_16x16x32_bf16 v[140:143], v[176:179], v[224:227], v[112:115]
	v_mfma_f32_16x16x32_bf16 v[112:115], v[164:167], v[212:215], v[128:131]
	v_mfma_f32_16x16x32_bf16 v[128:131], v[168:171], v[216:219], v[112:115]
	v_mfma_f32_16x16x32_bf16 v[112:115], v[172:175], v[212:215], v[124:127]
	v_mfma_f32_16x16x32_bf16 v[124:127], v[176:179], v[216:219], v[112:115]
	v_mfma_f32_16x16x32_bf16 v[112:115], v[164:167], v[204:207], v[116:119]
	v_mfma_f32_16x16x32_bf16 v[108:111], v[172:175], v[204:207], v[108:111]
	v_mfma_f32_16x16x32_bf16 v[104:107], v[164:167], v[196:199], v[104:107]
	v_mfma_f32_16x16x32_bf16 v[88:91], v[172:175], v[196:199], v[88:91]
	v_mfma_f32_16x16x32_bf16 v[116:119], v[168:171], v[208:211], v[112:115]
	v_mfma_f32_16x16x32_bf16 v[108:111], v[176:179], v[208:211], v[108:111]
	v_mfma_f32_16x16x32_bf16 v[104:107], v[168:171], v[200:203], v[104:107]
	v_mfma_f32_16x16x32_bf16 v[88:91], v[176:179], v[200:203], v[88:91]
	s_setprio 0
.LBB0_1285:
	s_add_u32 s40, s38, 0xfff80080
	s_addc_u32 s41, s39, -1
	s_cmp_eq_u32 s84, 28
	s_cselect_b32 s47, s29, s41
	s_cselect_b32 s46, s28, s40
	s_cselect_b32 s41, s37, s27
	s_cselect_b32 s40, s36, s16
	s_barrier
	s_mov_b32 m0, s45
	v_lshl_add_u64 v[2:3], s[40:41], 0, v[230:231]
	s_add_u32 s86, s40, 0x80000
	s_mov_b64 exec, s[34:35]
	s_cbranch_execz .Lq6_r2
	ds_read_b128 v[156:159], v249 offset:16384
	ds_read_b128 v[160:163], v249 offset:17408
	ds_read_b128 v[148:151], v249 offset:18432
	ds_read_b128 v[152:155], v249 offset:19456
	ds_read_b128 v[132:135], v249 offset:20480
	ds_read_b128 v[136:139], v249 offset:21504
	ds_read_b128 v[112:115], v249 offset:22528
	ds_read_b128 v[120:123], v249 offset:23552
.Lq6_r2:
	s_mov_b64 exec, -1
	global_load_lds_dwordx4 v[2:3], off
	v_lshl_add_u64 v[236:237], s[40:41], 0, v[228:229]
	s_mov_b32 m0, s48
	s_addc_u32 s87, s41, 0
	global_load_lds_dwordx4 v[236:237], off
	v_lshl_add_u64 v[196:197], s[86:87], 0, v[230:231]
	s_mov_b32 m0, s49
	v_lshl_add_u64 v[238:239], s[46:47], 0, v[230:231]
	s_mov_b64 exec, s[34:35]
	s_cbranch_execz .Lq6_s3
	global_load_lds_dwordx4 v[196:197], off
.Lq6_s3:
	s_mov_b64 exec, -1
	v_lshl_add_u64 v[196:197], s[86:87], 0, v[228:229]
	s_mov_b32 m0, s50
	v_lshl_add_u64 v[240:241], s[46:47], 0, v[228:229]
	s_mov_b64 exec, s[34:35]
	s_cbranch_execz .Lq6_s4
	global_load_lds_dwordx4 v[196:197], off
.Lq6_s4:
	s_mov_b64 exec, -1
	s_mov_b32 m0, s44
	s_and_b64 vcc, exec, s[4:5]
	global_load_lds_dwordx4 v[238:239], off
	s_mov_b32 m0, s51
	s_nop 0
	global_load_lds_dwordx4 v[240:241], off
	s_waitcnt vmcnt(8)
	s_cmp_eq_u64 s[34:35], 0
	s_cbranch_scc0 .Lq6_w2
	s_waitcnt vmcnt(4)
.Lq6_w2:
	s_waitcnt lgkmcnt(0)
	s_barrier
	s_cbranch_vccnz .LBB0_1287
	s_setprio 1
	s_waitcnt lgkmcnt(0)
	v_mfma_f32_16x16x32_bf16 v[64:67], v[180:183], v[156:159], v[64:67]
	v_mfma_f32_16x16x32_bf16 v[60:63], v[188:191], v[156:159], v[60:63]
	v_mfma_f32_16x16x32_bf16 v[48:51], v[180:183], v[148:151], v[48:51]
	v_mfma_f32_16x16x32_bf16 v[44:47], v[188:191], v[148:151], v[44:47]
	v_mfma_f32_16x16x32_bf16 v[32:35], v[180:183], v[132:135], v[32:35]
	v_mfma_f32_16x16x32_bf16 v[28:31], v[188:191], v[132:135], v[28:31]
	v_mfma_f32_16x16x32_bf16 v[16:19], v[180:183], v[112:115], v[16:19]
	v_mfma_f32_16x16x32_bf16 v[12:15], v[188:191], v[112:115], v[12:15]
	v_mfma_f32_16x16x32_bf16 v[64:67], v[184:187], v[160:163], v[64:67]
	v_mfma_f32_16x16x32_bf16 v[60:63], v[192:195], v[160:163], v[60:63]
	v_mfma_f32_16x16x32_bf16 v[48:51], v[184:187], v[152:155], v[48:51]
	v_mfma_f32_16x16x32_bf16 v[44:47], v[192:195], v[152:155], v[44:47]
	v_mfma_f32_16x16x32_bf16 v[32:35], v[184:187], v[136:139], v[32:35]
	v_mfma_f32_16x16x32_bf16 v[28:31], v[192:195], v[136:139], v[28:31]
	v_mfma_f32_16x16x32_bf16 v[16:19], v[184:187], v[120:123], v[16:19]
	v_mfma_f32_16x16x32_bf16 v[12:15], v[192:195], v[120:123], v[12:15]
	s_setprio 0
	s_setprio 1
	v_mfma_f32_16x16x32_bf16 v[56:59], v[164:167], v[156:159], v[56:59]
	v_mfma_f32_16x16x32_bf16 v[52:55], v[172:175], v[156:159], v[52:55]
	v_mfma_f32_16x16x32_bf16 v[40:43], v[164:167], v[148:151], v[40:43]
	v_mfma_f32_16x16x32_bf16 v[36:39], v[172:175], v[148:151], v[36:39]
	v_mfma_f32_16x16x32_bf16 v[24:27], v[164:167], v[132:135], v[24:27]
	v_mfma_f32_16x16x32_bf16 v[20:23], v[172:175], v[132:135], v[20:23]
	v_mfma_f32_16x16x32_bf16 v[8:11], v[164:167], v[112:115], v[8:11]
	v_mfma_f32_16x16x32_bf16 v[4:7], v[172:175], v[112:115], v[4:7]
	v_mfma_f32_16x16x32_bf16 v[56:59], v[168:171], v[160:163], v[56:59]
	v_mfma_f32_16x16x32_bf16 v[52:55], v[176:179], v[160:163], v[52:55]
	v_mfma_f32_16x16x32_bf16 v[40:43], v[168:171], v[152:155], v[40:43]
	v_mfma_f32_16x16x32_bf16 v[36:39], v[176:179], v[152:155], v[36:39]
	v_mfma_f32_16x16x32_bf16 v[24:27], v[168:171], v[136:139], v[24:27]
	v_mfma_f32_16x16x32_bf16 v[20:23], v[176:179], v[136:139], v[20:23]
	v_mfma_f32_16x16x32_bf16 v[8:11], v[168:171], v[120:123], v[8:11]
	v_mfma_f32_16x16x32_bf16 v[4:7], v[176:179], v[120:123], v[4:7]
	s_setprio 0
.LBB0_1287:
	s_barrier
	v_add_u32_e32 v1, 0x18000, v246
	ds_read_b128 v[180:183], v1
	ds_read_b128 v[184:187], v1 offset:1024
	ds_read_b128 v[188:191], v1 offset:2048
	ds_read_b128 v[192:195], v1 offset:3072
	v_add_u32_e32 v1, 0x1c000, v246
	s_mov_b64 exec, s[34:35]
	s_cbranch_execz .Lq6_r3
	ds_read_b128 v[164:167], v1
	ds_read_b128 v[168:171], v1 offset:1024
	ds_read_b128 v[172:175], v1 offset:2048
	ds_read_b128 v[176:179], v1 offset:3072
.Lq6_r3:
	s_mov_b64 exec, -1
	s_add_u32 s46, s46, 0x80000
	s_addc_u32 s47, s47, 0
	s_mov_b32 m0, s56
	s_waitcnt lgkmcnt(0)
	v_lshl_add_u64 v[112:113], s[46:47], 0, v[230:231]
	ds_read_b128 v[220:223], v249 offset:32768
	ds_read_b128 v[224:227], v249 offset:33792
	ds_read_b128 v[212:215], v249 offset:34816
	ds_read_b128 v[216:219], v249 offset:35840
	ds_read_b128 v[204:207], v249 offset:36864
	ds_read_b128 v[208:211], v249 offset:37888
	ds_read_b128 v[196:199], v249 offset:38912
	ds_read_b128 v[200:203], v249 offset:39936
	s_mov_b64 exec, s[34:35]
	s_cbranch_execz .Lq6_s5
	global_load_lds_dwordx4 v[112:113], off
.Lq6_s5:
	s_mov_b64 exec, -1
	v_lshl_add_u64 v[112:113], s[46:47], 0, v[228:229]
	s_mov_b32 m0, s57
	s_nop 0
	s_mov_b64 exec, s[34:35]
	s_cbranch_execz .Lq6_s6
	global_load_lds_dwordx4 v[112:113], off

.Lq6_w3:
	s_waitcnt lgkmcnt(0)
	s_barrier
	s_setprio 1
	s_waitcnt lgkmcnt(0)
	v_mfma_f32_16x16x32_bf16 v[68:71], v[180:183], v[220:223], v[68:71]
	v_mfma_f32_16x16x32_bf16 v[160:163], v[184:187], v[224:227], v[68:71]
	v_mfma_f32_16x16x32_bf16 v[68:71], v[188:191], v[220:223], v[72:75]
	v_mfma_f32_16x16x32_bf16 v[156:159], v[192:195], v[224:227], v[68:71]
	v_mfma_f32_16x16x32_bf16 v[68:71], v[180:183], v[212:215], v[76:79]
	v_mfma_f32_16x16x32_bf16 v[152:155], v[184:187], v[216:219], v[68:71]
	v_mfma_f32_16x16x32_bf16 v[68:71], v[188:191], v[212:215], v[80:83]
	v_mfma_f32_16x16x32_bf16 v[148:151], v[192:195], v[216:219], v[68:71]
	v_mfma_f32_16x16x32_bf16 v[68:71], v[180:183], v[204:207], v[84:87]
	v_mfma_f32_16x16x32_bf16 v[136:139], v[184:187], v[208:211], v[68:71]
	v_mfma_f32_16x16x32_bf16 v[68:71], v[188:191], v[204:207], v[92:95]
	v_mfma_f32_16x16x32_bf16 v[132:135], v[192:195], v[208:211], v[68:71]
	v_mfma_f32_16x16x32_bf16 v[68:71], v[180:183], v[196:199], v[96:99]
	v_mfma_f32_16x16x32_bf16 v[120:123], v[184:187], v[200:203], v[68:71]
	v_mfma_f32_16x16x32_bf16 v[68:71], v[188:191], v[196:199], v[100:103]
	v_mfma_f32_16x16x32_bf16 v[112:115], v[192:195], v[200:203], v[68:71]
	s_setprio 0
	s_and_b64 vcc, exec, s[4:5]
	s_cbranch_vccnz .LBB0_1289
	s_setprio 1
	v_mfma_f32_16x16x32_bf16 v[68:71], v[164:167], v[220:223], v[144:147]
	v_mfma_f32_16x16x32_bf16 v[144:147], v[168:171], v[224:227], v[68:71]
	v_mfma_f32_16x16x32_bf16 v[68:71], v[172:175], v[220:223], v[140:143]
	v_mfma_f32_16x16x32_bf16 v[140:143], v[176:179], v[224:227], v[68:71]
	v_mfma_f32_16x16x32_bf16 v[68:71], v[164:167], v[212:215], v[128:131]
	v_mfma_f32_16x16x32_bf16 v[128:131], v[168:171], v[216:219], v[68:71]
	v_mfma_f32_16x16x32_bf16 v[68:71], v[172:175], v[212:215], v[124:127]
	v_mfma_f32_16x16x32_bf16 v[124:127], v[176:179], v[216:219], v[68:71]
	v_mfma_f32_16x16x32_bf16 v[68:71], v[164:167], v[204:207], v[116:119]
	v_mfma_f32_16x16x32_bf16 v[116:119], v[168:171], v[208:211], v[68:71]
	v_mfma_f32_16x16x32_bf16 v[68:71], v[172:175], v[204:207], v[108:111]
	v_mfma_f32_16x16x32_bf16 v[108:111], v[176:179], v[208:211], v[68:71]
	v_mfma_f32_16x16x32_bf16 v[68:71], v[164:167], v[196:199], v[104:107]
	v_mfma_f32_16x16x32_bf16 v[104:107], v[168:171], v[200:203], v[68:71]
	v_mfma_f32_16x16x32_bf16 v[68:71], v[172:175], v[196:199], v[88:91]
	v_mfma_f32_16x16x32_bf16 v[88:91], v[176:179], v[200:203], v[68:71]
	s_setprio 0
.LBB0_1289:
	s_barrier
	s_mov_b32 m0, s61
	v_lshl_add_u64 v[2:3], v[2:3], 0, s[14:15]
	s_add_u32 s40, s40, 0x80080
	s_mov_b64 exec, s[34:35]
	s_cbranch_execz .Lq6_r4
	ds_read_b128 v[96:99], v249 offset:49152
	ds_read_b128 v[100:103], v249 offset:50176
	ds_read_b128 v[84:87], v249 offset:51200
	ds_read_b128 v[92:95], v249 offset:52224
	ds_read_b128 v[76:79], v249 offset:53248
	ds_read_b128 v[80:83], v249 offset:54272
	ds_read_b128 v[68:71], v249 offset:55296
	ds_read_b128 v[72:75], v249 offset:56320
.Lq6_r4:
	s_mov_b64 exec, -1
	global_load_lds_dwordx4 v[2:3], off
	v_lshl_add_u64 v[2:3], v[236:237], 0, s[14:15]
	s_mov_b32 m0, s62
	s_addc_u32 s41, s41, 0
	global_load_lds_dwordx4 v[2:3], off
	v_lshl_add_u64 v[2:3], s[40:41], 0, v[230:231]
	s_mov_b32 m0, s65
	s_and_b64 vcc, exec, s[4:5]
	s_mov_b64 exec, s[34:35]
	s_cbranch_execz .Lq6_s7
	global_load_lds_dwordx4 v[2:3], off
.Lq6_s7:
	s_mov_b64 exec, -1
	v_lshl_add_u64 v[2:3], s[40:41], 0, v[228:229]
	s_mov_b32 m0, s66
	s_nop 0
	s_mov_b64 exec, s[34:35]
	s_cbranch_execz .Lq6_s8
	global_load_lds_dwordx4 v[2:3], off
.Lq6_s8:
	s_mov_b64 exec, -1
	v_lshl_add_u64 v[2:3], v[238:239], 0, s[14:15]
	s_mov_b32 m0, s63
	s_nop 0
	global_load_lds_dwordx4 v[2:3], off
	v_lshl_add_u64 v[2:3], v[240:241], 0, s[14:15]
	s_mov_b32 m0, s64
	s_nop 0
	global_load_lds_dwordx4 v[2:3], off
	s_waitcnt vmcnt(8)
	s_cmp_eq_u64 s[34:35], 0
	s_cbranch_scc0 .Lq6_w4
	s_waitcnt vmcnt(4)
.Lq6_w4:
	s_waitcnt lgkmcnt(0)
	s_barrier
	s_cbranch_vccnz .LBB0_1282
	s_setprio 1
	s_waitcnt lgkmcnt(0)
	v_mfma_f32_16x16x32_bf16 v[64:67], v[180:183], v[96:99], v[64:67]
	v_mfma_f32_16x16x32_bf16 v[60:63], v[188:191], v[96:99], v[60:63]
	v_mfma_f32_16x16x32_bf16 v[48:51], v[180:183], v[84:87], v[48:51]
	v_mfma_f32_16x16x32_bf16 v[44:47], v[188:191], v[84:87], v[44:47]
	v_mfma_f32_16x16x32_bf16 v[32:35], v[180:183], v[76:79], v[32:35]
	v_mfma_f32_16x16x32_bf16 v[28:31], v[188:191], v[76:79], v[28:31]
	v_mfma_f32_16x16x32_bf16 v[16:19], v[180:183], v[68:71], v[16:19]
	v_mfma_f32_16x16x32_bf16 v[12:15], v[188:191], v[68:71], v[12:15]
	v_mfma_f32_16x16x32_bf16 v[64:67], v[184:187], v[100:103], v[64:67]
	v_mfma_f32_16x16x32_bf16 v[60:63], v[192:195], v[100:103], v[60:63]
	v_mfma_f32_16x16x32_bf16 v[48:51], v[184:187], v[92:95], v[48:51]
	v_mfma_f32_16x16x32_bf16 v[44:47], v[192:195], v[92:95], v[44:47]
	v_mfma_f32_16x16x32_bf16 v[32:35], v[184:187], v[80:83], v[32:35]
	v_mfma_f32_16x16x32_bf16 v[28:31], v[192:195], v[80:83], v[28:31]
	v_mfma_f32_16x16x32_bf16 v[16:19], v[184:187], v[72:75], v[16:19]
	v_mfma_f32_16x16x32_bf16 v[12:15], v[192:195], v[72:75], v[12:15]
	s_setprio 0
	s_setprio 1
	v_mfma_f32_16x16x32_bf16 v[56:59], v[164:167], v[96:99], v[56:59]
	v_mfma_f32_16x16x32_bf16 v[52:55], v[172:175], v[96:99], v[52:55]
	v_mfma_f32_16x16x32_bf16 v[40:43], v[164:167], v[84:87], v[40:43]
	v_mfma_f32_16x16x32_bf16 v[36:39], v[172:175], v[84:87], v[36:39]
	v_mfma_f32_16x16x32_bf16 v[24:27], v[164:167], v[76:79], v[24:27]
	v_mfma_f32_16x16x32_bf16 v[20:23], v[172:175], v[76:79], v[20:23]
	v_mfma_f32_16x16x32_bf16 v[8:11], v[164:167], v[68:71], v[8:11]
	v_mfma_f32_16x16x32_bf16 v[2:5], v[172:175], v[68:71], v[4:7]
	v_mfma_f32_16x16x32_bf16 v[56:59], v[168:171], v[100:103], v[56:59]
	v_mfma_f32_16x16x32_bf16 v[52:55], v[176:179], v[100:103], v[52:55]
	v_mfma_f32_16x16x32_bf16 v[40:43], v[168:171], v[92:95], v[40:43]
	v_mfma_f32_16x16x32_bf16 v[36:39], v[176:179], v[92:95], v[36:39]
	v_mfma_f32_16x16x32_bf16 v[24:27], v[168:171], v[80:83], v[24:27]
	v_mfma_f32_16x16x32_bf16 v[20:23], v[176:179], v[80:83], v[20:23]
	v_mfma_f32_16x16x32_bf16 v[8:11], v[168:171], v[72:75], v[8:11]
	v_mfma_f32_16x16x32_bf16 v[4:7], v[176:179], v[72:75], v[2:5]
	s_setprio 0
	s_branch .LBB0_1282
